# LN1 row loop: gamma/beta hoisted, modulation vectors resident, next-row prefetch; final LN loop next-row prefetch; scan ctx prefix loads batched
# speedup vs baseline: 1.0150x; 1.0147x over previous
; __device__ __forceinline__ void phase_ln_mod1(Frame& F) {
;     const int gw = F.bid * 8 + F.wave, NGW = F.G * 8; const float* mod = (const float*)(F.ws + WS_MOD) + 3 * 3072;
;     for (int row = gw; row < RT; row += NGW) {
;         const bool isctx = row >= RL; const int rho = isctx ? 2 : row / SEQ;
;         float* src = F.out + (size_t)row * D;
;         f32x4 v[4];
;         if (isctx) { const float* mod0 = (const float*)(F.ws + WS_MOD);
; #pragma unroll
;             for (int j = 0; j < 4; ++j) { const int idx = 256 * j + 4 * F.lane; f32x4 a = {0.f, 0.f, 0.f, 0.f};
; #pragma unroll
;                 for (int ks = 0; ks < 8; ++ks) a += *(const f32x4*)((const float*)(F.ws + WS_Y1S) + (((((size_t)ks * 2 + ((row - RL) >> 8)) * 4 + j) * 256 + ((row - RL) & 255)) * 256) + 4 * F.lane);
;                 v[j] = DN_ALPHA * *(const f32x4*)(F.in[I_CTX] + (size_t)(row - RL) * D + idx) + *(const f32x4*)(mod0 + 2 * 3072 + 2048 + idx) * a; } }
;         else {
; #pragma unroll
;             for (int j = 0; j < 4; ++j) { const int idx = 256 * j + 4 * F.lane; const size_t fv_ = ((((size_t)(row >> 8) * 4 + j) * 256 + (row & 255)) * 512) + 8 * F.lane;
;                 const u32x2 f = __builtin_nontemporal_load((const u32x2*)((const char*)F.out + (fv_ >> 11) * 4096 + (fv_ & 2047)));
;                 const f32x4 fv = {bf2f(f.x), bf2f(f.x >> 16), bf2f(f.y), bf2f(f.y >> 16)};
;                 v[j] = DN_ALPHA * __builtin_nontemporal_load((const f32x4*)(F.in[I_X] + (size_t)row * D + idx)) + fv; } }
.LBB0_330:
	s_cmp_lt_i32 s26, 5
	s_cselect_b64 s[0:1], -1, 0
	s_and_b64 s[4:5], s[0:1], s[4:5]
	s_andn2_b64 vcc, exec, s[4:5]
	s_cbranch_vccnz .LBB0_343
	s_lshl_b32 s0, s92, 3
	v_readlane_b32 s1, v253, 23
	s_add_i32 s6, s0, s1
	s_cmp_gt_i32 s6, 0x81ff
	s_cbranch_scc1 .LBB0_343
	v_mbcnt_lo_u32_b32 v1, -1, 0
	v_mbcnt_hi_u32_b32 v2, -1, v1
	v_and_b32_e32 v1, 64, v2
	v_add_u32_e32 v3, 64, v1
	v_xor_b32_e32 v1, 1, v2
	v_cmp_lt_i32_e32 vcc, v1, v3
	v_xor_b32_e32 v4, 2, v2
	s_lshl_b32 s8, s84, 3
	v_cndmask_b32_e32 v1, v2, v1, vcc
	v_cmp_lt_i32_e32 vcc, v4, v3
	v_mov_b32_e32 v59, 0
	s_add_u32 s2, s56, 0x109000
	v_cndmask_b32_e32 v4, v2, v4, vcc
	v_lshlrev_b32_e32 v98, 2, v4
	v_xor_b32_e32 v4, 4, v2
	v_cmp_lt_i32_e32 vcc, v4, v3
	v_mov_b32_e32 v5, v59
	s_addc_u32 s3, s57, 0
	v_cndmask_b32_e32 v4, v2, v4, vcc
	v_lshlrev_b32_e32 v99, 2, v4
	v_xor_b32_e32 v4, 8, v2
	v_cmp_lt_i32_e32 vcc, v4, v3
	s_mov_b64 s[0:1], 0x12600000
	v_mov_b32_e32 v15, v59
	v_cndmask_b32_e32 v4, v2, v4, vcc
	v_lshlrev_b32_e32 v100, 2, v4
	v_xor_b32_e32 v4, 16, v2
	v_cmp_lt_i32_e32 vcc, v4, v3
	v_mov_b32_e32 v17, v59
	v_readlane_b32 s12, v253, 7
	v_cndmask_b32_e32 v4, v2, v4, vcc
	v_lshlrev_b32_e32 v101, 2, v4
	v_xor_b32_e32 v4, 32, v2
	v_cmp_lt_i32_e32 vcc, v4, v3
	v_readlane_b32 s7, v253, 23
	v_readlane_b32 s18, v253, 13
	v_cndmask_b32_e32 v2, v2, v4, vcc
	v_lshlrev_b32_e32 v4, 4, v209
	v_lshlrev_b32_e32 v102, 2, v2
	v_lshlrev_b32_e32 v2, 2, v209
	v_lshl_add_u64 v[12:13], s[56:57], 0, v[4:5]
	v_or_b32_e32 v6, 0x100, v2
	v_or_b32_e32 v8, 0x200, v2
	v_or_b32_e32 v10, 0x300, v2
	v_lshl_add_u64 v[62:63], v[12:13], 0, s[0:1]
	s_add_u32 s0, s56, 0x108000
	s_addc_u32 s1, s57, 0
	v_lshlrev_b32_e32 v12, 2, v6
	v_mov_b32_e32 v13, v59
	v_lshlrev_b32_e32 v14, 2, v8
	v_lshlrev_b32_e32 v16, 2, v10
	v_lshl_add_u64 v[64:65], s[0:1], 0, v[4:5]
	v_lshl_add_u64 v[66:67], s[0:1], 0, v[12:13]
	v_lshl_add_u64 v[68:69], s[0:1], 0, v[14:15]
	v_lshl_add_u64 v[70:71], s[0:1], 0, v[16:17]
	s_lshl_b32 s0, s92, 12
	s_lshl_b32 s1, s7, 9
	v_lshlrev_b32_e32 v58, 3, v209
	v_lshrrev_b32_e32 v3, 4, v209
	v_readlane_b32 s21, v253, 16
	s_add_i32 s18, s0, s1
	s_lshl_b32 s0, s92, 11
	s_lshl_b32 s1, s7, 8
	s_ashr_i32 s7, s6, 31
	v_mul_u32_u24_e32 v18, 0x410000, v3
	v_and_b32_e32 v3, 0x78, v58
	s_add_i32 s21, s0, s1
	s_lshl_b64 s[0:1], s[6:7], 7
	v_lshl_add_u64 v[60:61], s[36:37], 0, v[4:5]
	v_mov_b32_e32 v19, v59
	v_lshl_add_u64 v[72:73], s[40:41], 0, v[4:5]
	v_lshl_add_u64 v[74:75], s[48:49], 0, v[4:5]
	v_lshl_add_u64 v[76:77], s[50:51], 0, v[4:5]
	v_or_b32_e32 v4, s0, v3
	v_mov_b32_e32 v5, s1
	v_lshl_add_u64 v[4:5], v[4:5], 0, v[18:19]
	v_readlane_b32 s13, v253, 8
	v_readlane_b32 s14, v253, 9
	v_readlane_b32 s15, v253, 10
	v_readlane_b32 s16, v253, 11
	v_readlane_b32 s17, v253, 12
	v_readlane_b32 s19, v253, 14
	v_readlane_b32 s20, v253, 15
	v_readlane_b32 s24, v253, 19
	v_readlane_b32 s25, v253, 20
	v_readlane_b32 s26, v253, 21
	v_readlane_b32 s27, v253, 22
	v_lshl_add_u64 v[4:5], s[56:57], 0, v[4:5]
	s_mov_b64 s[0:1], 0x6200000
	s_ashr_i32 s9, s8, 31
	s_mov_b32 s11, 0
	v_lshlrev_b32_e32 v1, 2, v1
	v_lshl_add_u64 v[78:79], s[48:49], 0, v[12:13]
	v_lshl_add_u64 v[80:81], s[50:51], 0, v[12:13]
	v_lshl_add_u64 v[82:83], s[48:49], 0, v[14:15]
	v_lshl_add_u64 v[84:85], s[50:51], 0, v[14:15]
	v_lshl_add_u64 v[86:87], s[48:49], 0, v[16:17]
	v_lshl_add_u64 v[88:89], s[50:51], 0, v[16:17]
	v_lshl_add_u64 v[90:91], s[26:27], 0, v[58:59]
	s_lshl_b32 s19, s84, 12
	s_lshl_b32 s24, s84, 11
	v_lshl_add_u64 v[92:93], v[4:5], 0, s[0:1]
	s_lshl_b64 s[12:13], s[8:9], 7
	s_lshl_b64 s[14:15], s[6:7], 12
	s_lshl_b64 s[16:17], s[8:9], 12
	s_mov_b32 s20, 0x3fb504f3
	s_mov_b32 s7, 0x40000
	s_mov_b32 s9, 0x80000
	s_mov_b32 s25, 0xc0000
	v_mov_b32_e32 v103, 0x3727c5ac
	s_mov_b32 s26, 0xf800000
	v_mov_b32_e32 v104, 0x260
	v_lshlrev_b32_e32 v105, 2, v2
	v_lshlrev_b32_e32 v106, 2, v6
	v_lshlrev_b32_e32 v107, 2, v8
	v_lshlrev_b32_e32 v108, 2, v10
	s_mov_b32 s27, 0x1040000
	s_mov_b32 s28, 0x2080000
	v_readlane_b32 s22, v253, 17
	v_readlane_b32 s23, v253, 18
	global_load_dwordx4 v[214:217], v[74:75], off
	global_load_dwordx4 v[218:221], v[76:77], off
	global_load_dwordx4 v[222:225], v[78:79], off
	global_load_dwordx4 v[226:229], v[80:81], off
	global_load_dwordx4 v[230:233], v[82:83], off
	global_load_dwordx4 v[234:237], v[84:85], off
	global_load_dwordx4 v[238:241], v[86:87], off
	global_load_dwordx4 v[242:245], v[88:89], off
	v_readlane_b32 s98, v253, 21
	v_readlane_b32 s99, v253, 22
	s_mov_b32 s100, -1
	s_nop 3
	s_ashr_i32 s0, s6, 8
	s_ashr_i32 s1, s0, 31
	s_and_b32 s10, s18, 0x1f800
	s_lshl_b64 s[0:1], s[0:1], 20
	s_lshl_b32 s10, s10, 1
	s_or_b32 s0, s0, s10
	s_add_u32 s0, s98, s0
	s_addc_u32 s1, s99, s1
	s_and_b32 s10, s18, 0x600
	s_add_u32 s0, s0, s10
	s_addc_u32 s1, s1, 0
	v_lshl_add_u64 v[168:169], s[0:1], 0, v[58:59]
	v_add_co_u32_e32 v170, vcc, s7, v168
	global_load_dwordx2 v[142:143], v[168:169], off nt
	s_nop 0
	v_addc_co_u32_e32 v171, vcc, 0, v169, vcc
	global_load_dwordx2 v[144:145], v[170:171], off nt
	v_add_co_u32_e32 v170, vcc, s9, v168
	v_lshl_add_u64 v[172:173], v[60:61], 0, s[14:15]
	s_nop 0
	v_addc_co_u32_e32 v171, vcc, 0, v169, vcc
	global_load_dwordx4 v[150:153], v[172:173], off nt
	v_add_co_u32_e32 v168, vcc, s25, v168
	global_load_dwordx2 v[146:147], v[170:171], off nt
	s_nop 0
	v_addc_co_u32_e32 v169, vcc, 0, v169, vcc
	global_load_dwordx2 v[148:149], v[168:169], off nt
	s_nop 0
	global_load_dwordx4 v[154:157], v[172:173], off offset:1024 nt
	global_load_dwordx4 v[158:161], v[172:173], off offset:2048 nt
	global_load_dwordx4 v[162:165], v[172:173], off offset:3072 nt
; __device__ __forceinline__ void ln_row(f32x4 (&v)[4], const float* g, const float* b, int lane) {
;     float s = 0.f;
; #pragma unroll
;     for (int j = 0; j < 4; ++j) s += (v[j][0] + v[j][1]) + (v[j][2] + v[j][3]);
;     const float mean = wave_sum(s) * (1.f / D); float s2 = 0.f;
; __device__ __forceinline__ void phase_ln_mod1(Frame& F) {
;     ...
;     for (int row = gw; row < RT; row += NGW) {
;         const bool isctx = row >= RL; const int rho = isctx ? 2 : row / SEQ;
;         float* src = F.out + (size_t)row * D;
;         f32x4 v[4];
;         if (isctx) { const float* mod0 = (const float*)(F.ws + WS_MOD);
; #pragma unroll
;             for (int j = 0; j < 4; ++j) { const int idx = 256 * j + 4 * F.lane; f32x4 a = {0.f, 0.f, 0.f, 0.f};
; #pragma unroll
;                 for (int ks = 0; ks < 8; ++ks) a += *(const f32x4*)((const float*)(F.ws + WS_Y1S) + (((((size_t)ks * 2 + ((row - RL) >> 8)) * 4 + j) * 256 + ((row - RL) & 255)) * 256) + 4 * F.lane);
;                 v[j] = DN_ALPHA * *(const f32x4*)(F.in[I_CTX] + (size_t)(row - RL) * D + idx) + *(const f32x4*)(mod0 + 2 * 3072 + 2048 + idx) * a; } }
;         else {
; #pragma unroll
;             for (int j = 0; j < 4; ++j) { const int idx = 256 * j + 4 * F.lane; const size_t fv_ = ((((size_t)(row >> 8) * 4 + j) * 256 + (row & 255)) * 512) + 8 * F.lane;
;                 const u32x2 f = __builtin_nontemporal_load((const u32x2*)((const char*)F.out + (fv_ >> 11) * 4096 + (fv_ & 2047)));
;                 const f32x4 fv = {bf2f(f.x), bf2f(f.x >> 16), bf2f(f.y), bf2f(f.y >> 16)};
;                 v[j] = DN_ALPHA * __builtin_nontemporal_load((const f32x4*)(F.in[I_X] + (size_t)row * D + idx)) + fv; } }
.Lp4_loop:
	s_ashr_i32 s0, s6, 14
	s_cmp_eq_u32 s0, s100
	s_cbranch_scc1 .Lp4_modok
	s_mov_b32 s100, s0
	s_mul_i32 s22, s0, 0xc00
	s_mov_b32 s23, 0
	s_lshl_b64 s[0:1], s[22:23], 2
	s_add_u32 s0, s2, s0
	s_addc_u32 s1, s3, s1
	s_add_u32 s22, s0, 0x1000
	s_addc_u32 s23, s1, 0
	global_load_dwordx4 v[110:113], v105, s[22:23]
	global_load_dwordx4 v[114:117], v106, s[22:23]
	global_load_dwordx4 v[118:121], v107, s[22:23]
	global_load_dwordx4 v[122:125], v108, s[22:23]
	global_load_dwordx4 v[126:129], v105, s[0:1]
	global_load_dwordx4 v[130:133], v106, s[0:1]
	global_load_dwordx4 v[134:137], v107, s[0:1]
	global_load_dwordx4 v[138:141], v108, s[0:1]
	s_waitcnt vmcnt(0)
	v_pk_add_f32 v[110:111], v[110:111], 1.0 op_sel_hi:[1,0]
	v_pk_add_f32 v[112:113], v[112:113], 1.0 op_sel_hi:[1,0]
	v_pk_add_f32 v[114:115], v[114:115], 1.0 op_sel_hi:[1,0]
	v_pk_add_f32 v[116:117], v[116:117], 1.0 op_sel_hi:[1,0]
	v_pk_add_f32 v[118:119], v[118:119], 1.0 op_sel_hi:[1,0]
	v_pk_add_f32 v[120:121], v[120:121], 1.0 op_sel_hi:[1,0]
	v_pk_add_f32 v[122:123], v[122:123], 1.0 op_sel_hi:[1,0]
	v_pk_add_f32 v[124:125], v[124:125], 1.0 op_sel_hi:[1,0]
.Lp4_modok:
	s_waitcnt vmcnt(8)
	v_mov_b32_e32 v14, v142
	v_mov_b32_e32 v15, v143
	v_mov_b32_e32 v22, v144
	v_mov_b32_e32 v23, v145
	v_mov_b32_e32 v24, v146
	v_mov_b32_e32 v25, v147
	v_mov_b32_e32 v26, v148
	v_mov_b32_e32 v27, v149
	v_mov_b32_e32 v2, v150
	v_mov_b32_e32 v3, v151
	v_mov_b32_e32 v4, v152
	v_mov_b32_e32 v5, v153
	v_mov_b32_e32 v6, v154
	v_mov_b32_e32 v7, v155
	v_mov_b32_e32 v8, v156
	v_mov_b32_e32 v9, v157
	v_mov_b32_e32 v10, v158
	v_mov_b32_e32 v11, v159
	v_mov_b32_e32 v12, v160
	v_mov_b32_e32 v13, v161
	v_mov_b32_e32 v18, v162
	v_mov_b32_e32 v19, v163
	v_mov_b32_e32 v20, v164
	v_mov_b32_e32 v21, v165
	s_add_i32 s101, s6, s8
	s_cmp_lt_i32 s101, 0x8000
	s_cbranch_scc0 .Lp4_nopf
	s_add_i32 s11, s18, s19
	v_lshl_add_u64 v[166:167], v[60:61], 0, s[16:17]
	s_ashr_i32 s0, s101, 8
	s_ashr_i32 s1, s0, 31
	s_and_b32 s10, s11, 0x1f800
	s_lshl_b64 s[0:1], s[0:1], 20
	s_lshl_b32 s10, s10, 1
	s_or_b32 s0, s0, s10
	s_add_u32 s0, s98, s0
	s_addc_u32 s1, s99, s1
	s_and_b32 s10, s11, 0x600
	s_add_u32 s0, s0, s10
	s_addc_u32 s1, s1, 0
	v_lshl_add_u64 v[168:169], s[0:1], 0, v[58:59]
	v_add_co_u32_e32 v170, vcc, s7, v168
	global_load_dwordx2 v[142:143], v[168:169], off nt
	s_nop 0
	v_addc_co_u32_e32 v171, vcc, 0, v169, vcc
	global_load_dwordx2 v[144:145], v[170:171], off nt
	v_add_co_u32_e32 v170, vcc, s9, v168
	v_lshl_add_u64 v[172:173], v[166:167], 0, s[14:15]
	s_nop 0
	v_addc_co_u32_e32 v171, vcc, 0, v169, vcc
	global_load_dwordx4 v[150:153], v[172:173], off nt
	v_add_co_u32_e32 v168, vcc, s25, v168
	global_load_dwordx2 v[146:147], v[170:171], off nt
	s_nop 0
	v_addc_co_u32_e32 v169, vcc, 0, v169, vcc
	global_load_dwordx2 v[148:149], v[168:169], off nt
	s_nop 0
	global_load_dwordx4 v[154:157], v[172:173], off offset:1024 nt
	global_load_dwordx4 v[158:161], v[172:173], off offset:2048 nt
	global_load_dwordx4 v[162:165], v[172:173], off offset:3072 nt
	s_mov_b32 s11, 0
.Lp4_nopf:
	v_lshlrev_b32_e32 v16, 16, v14
	v_and_b32_e32 v17, 0xffff0000, v14
	v_lshlrev_b32_e32 v14, 16, v15
	v_and_b32_e32 v15, 0xffff0000, v15
	v_pk_fma_f32 v[4:5], v[4:5], s[20:21], v[14:15] op_sel_hi:[1,0,1]
	v_pk_fma_f32 v[2:3], v[2:3], s[20:21], v[16:17] op_sel_hi:[1,0,1]
	v_lshlrev_b32_e32 v14, 16, v22
	v_and_b32_e32 v15, 0xffff0000, v22
	v_lshlrev_b32_e32 v16, 16, v23
	v_and_b32_e32 v17, 0xffff0000, v23
	v_lshlrev_b32_e32 v22, 16, v24
	v_and_b32_e32 v23, 0xffff0000, v24
	v_lshlrev_b32_e32 v24, 16, v25
	v_and_b32_e32 v25, 0xffff0000, v25
	v_lshlrev_b32_e32 v28, 16, v26
	v_and_b32_e32 v29, 0xffff0000, v26
	v_lshlrev_b32_e32 v26, 16, v27
	v_and_b32_e32 v27, 0xffff0000, v27
	v_pk_fma_f32 v[8:9], v[8:9], s[20:21], v[16:17] op_sel_hi:[1,0,1]
	v_pk_fma_f32 v[6:7], v[6:7], s[20:21], v[14:15] op_sel_hi:[1,0,1]
	v_pk_fma_f32 v[14:15], v[12:13], s[20:21], v[24:25] op_sel_hi:[1,0,1]
	v_pk_fma_f32 v[16:17], v[10:11], s[20:21], v[22:23] op_sel_hi:[1,0,1]
	v_pk_fma_f32 v[12:13], v[20:21], s[20:21], v[26:27] op_sel_hi:[1,0,1]
	v_pk_fma_f32 v[10:11], v[18:19], s[20:21], v[28:29] op_sel_hi:[1,0,1]
	v_mov_b32_e32 v23, v5
	v_mov_b32_e32 v25, v4
	v_mov_b32_e32 v24, v3
	v_mov_b32_e32 v19, v9
	v_mov_b32_e32 v21, v8
	v_mov_b32_e32 v20, v7
	v_mov_b32_e32 v18, v6
	v_mov_b32_e32 v22, v2
	v_pk_add_f32 v[22:23], v[24:25], v[22:23]
	v_pk_add_f32 v[18:19], v[20:21], v[18:19]
	v_add_f32_e32 v22, v22, v23
	v_pk_add_f32 v[18:19], v[18:19], v[18:19] op_sel_hi:[0,1]
	v_add_f32_e32 v23, 0, v22
	v_add_f32_e32 v21, v16, v17
	v_add_f32_e32 v25, v14, v15
	v_mov_b32_e32 v20, v10
	v_mov_b32_e32 v24, v11
	v_mov_b32_e32 v18, v12
	v_mov_b32_e32 v22, v13
	v_pk_add_f32 v[20:21], v[20:21], v[24:25]
	v_pk_add_f32 v[18:19], v[18:19], v[22:23]
	s_nop 0
	v_pk_add_f32 v[18:19], v[20:21], v[18:19]
	s_nop 0
	v_add_f32_e32 v18, v18, v19
	ds_bpermute_b32 v19, v1, v18
	s_waitcnt lgkmcnt(0)
	v_add_f32_e32 v18, v18, v19
	ds_bpermute_b32 v19, v98, v18
	s_waitcnt lgkmcnt(0)
	v_add_f32_e32 v18, v18, v19
	ds_bpermute_b32 v19, v99, v18
	s_waitcnt lgkmcnt(0)
	v_add_f32_e32 v18, v18, v19
	ds_bpermute_b32 v19, v100, v18
	s_waitcnt lgkmcnt(0)
	v_add_f32_e32 v18, v18, v19
	ds_bpermute_b32 v19, v101, v18
	s_waitcnt lgkmcnt(0)
	v_add_f32_e32 v18, v18, v19
	ds_bpermute_b32 v19, v102, v18
	s_waitcnt lgkmcnt(0)
; __device__ __forceinline__ void ln_row(f32x4 (&v)[4], const float* g, const float* b, int lane) {
;     ...
; #pragma unroll
;     for (int j = 0; j < 4; ++j) { v[j] = v[j] - mean; s2 += (v[j][0] * v[j][0] + v[j][1] * v[j][1]) + (v[j][2] * v[j][2] + v[j][3] * v[j][3]); }
;     const float rstd = 1.0f / sqrtf(wave_sum(s2) * (1.f / D) + LN_EPS);
; #pragma unroll
;     for (int j = 0; j < 4; ++j) { const int idx = 256 * j + 4 * lane; v[j] = v[j] * rstd * *(const f32x4*)(g + idx) + *(const f32x4*)(b + idx); }
; }
; __device__ __forceinline__ void phase_ln_mod1(Frame& F) {
;     ...
;         ln_row(v, F.in[I_LNG], F.in[I_LNB], F.lane);
;         if (!isctx) {
; #pragma unroll
;             for (int j = 0; j < 4; ++j) { u32x2 w; w.x = pk2(v[j][0], v[j][1]); w.y = pk2(v[j][2], v[j][3]); __builtin_nontemporal_store(w, (u32x2*)((char*)src + 2048 + (256 * j + 4 * F.lane) * 2)); } }
; #pragma unroll
;         for (int j = 0; j < 4; ++j) { const int idx = 256 * j + 4 * F.lane;
;             const f32x4 sh = *(const f32x4*)(mod + rho * 3072 + idx), sc = *(const f32x4*)(mod + rho * 3072 + 1024 + idx);
;             v[j] = v[j] * (1.0f + sc) + sh; }
;         store_row_blk64((char*)F.ws + WS_HX, (size_t)row, F.lane, v);
;     }
	v_add_f32_e32 v28, v18, v19
	v_fmamk_f32 v3, v28, 0xba800000, v3
	v_fmamk_f32 v2, v28, 0xba800000, v2
	v_fmamk_f32 v5, v28, 0xba800000, v5
	v_fmac_f32_e32 v4, 0xba800000, v28
	v_fmamk_f32 v7, v28, 0xba800000, v7
	v_fmamk_f32 v6, v28, 0xba800000, v6
	v_fmamk_f32 v9, v28, 0xba800000, v9
	v_fmac_f32_e32 v8, 0xba800000, v28
	v_fmamk_f32 v48, v28, 0xba800000, v16
	v_pk_mul_f32 v[18:19], v[4:5], v[4:5]
	v_pk_mul_f32 v[20:21], v[2:3], v[2:3]
	v_pk_mul_f32 v[22:23], v[8:9], v[8:9]
	v_pk_mul_f32 v[24:25], v[6:7], v[6:7]
	v_fmamk_f32 v49, v28, 0xba800000, v17
	v_mul_f32_e32 v16, v48, v48
	v_pk_mov_b32 v[26:27], v[20:21], v[18:19] op_sel:[1,0]
	v_mov_b32_e32 v21, v19
	v_pk_mov_b32 v[18:19], v[24:25], v[22:23] op_sel:[1,0]
	v_mov_b32_e32 v25, v23
	v_fmac_f32_e32 v14, 0xba800000, v28
	v_pk_fma_f32 v[16:17], v[48:49], v[48:49], v[16:17] op_sel_hi:[1,1,0]
	v_pk_add_f32 v[20:21], v[26:27], v[20:21]
	v_pk_add_f32 v[18:19], v[18:19], v[24:25]
	v_fmamk_f32 v15, v28, 0xba800000, v15
	v_mul_f32_e32 v16, v14, v14
	v_pk_add_f32 v[20:21], v[20:21], v[20:21] op_sel_hi:[0,1]
	v_pk_add_f32 v[18:19], v[18:19], v[18:19] op_sel_hi:[0,1]
	v_pk_fma_f32 v[22:23], v[14:15], v[14:15], v[16:17] op_sel_hi:[1,1,0]
	v_fmamk_f32 v51, v28, 0xba800000, v13
	v_fmamk_f32 v50, v28, 0xba800000, v12
	v_fmamk_f32 v11, v28, 0xba800000, v11
	v_fmac_f32_e32 v10, 0xba800000, v28
	v_mul_f32_e32 v16, v10, v10
	v_mul_f32_e32 v22, v11, v11
	v_mul_f32_e32 v20, v50, v50
	v_mul_f32_e32 v18, v51, v51
	v_pk_add_f32 v[12:13], v[16:17], v[22:23]
	v_pk_add_f32 v[16:17], v[20:21], v[18:19]
	s_nop 0
	v_pk_add_f32 v[12:13], v[12:13], v[16:17]
	v_add_f32_e32 v12, v12, v13
	ds_bpermute_b32 v13, v1, v12
	s_waitcnt lgkmcnt(0)
	v_add_f32_e32 v12, v12, v13
	ds_bpermute_b32 v13, v98, v12
	s_waitcnt lgkmcnt(0)
	v_add_f32_e32 v12, v12, v13
	ds_bpermute_b32 v13, v99, v12
	s_waitcnt lgkmcnt(0)
	v_add_f32_e32 v12, v12, v13
	ds_bpermute_b32 v13, v100, v12
	s_waitcnt lgkmcnt(0)
	v_add_f32_e32 v12, v12, v13
	ds_bpermute_b32 v13, v101, v12
	s_waitcnt lgkmcnt(0)
	v_add_f32_e32 v12, v12, v13
	ds_bpermute_b32 v13, v102, v12
	s_waitcnt lgkmcnt(0)
	v_add_f32_e32 v12, v12, v13
	v_fmamk_f32 v12, v12, 0x3a800000, v103
	v_mul_f32_e32 v13, 0x4f800000, v12
	v_cmp_gt_f32_e32 vcc, s26, v12
	s_nop 1
	v_cndmask_b32_e32 v12, v12, v13, vcc
	v_sqrt_f32_e32 v13, v12
	s_nop 0
	v_add_u32_e32 v52, -1, v13
	v_fma_f32 v54, -v52, v13, v12
	v_add_u32_e32 v53, 1, v13
	v_cmp_ge_f32_e64 s[0:1], 0, v54
	s_nop 1
	v_cndmask_b32_e64 v52, v13, v52, s[0:1]
	v_fma_f32 v13, -v53, v13, v12
	v_cmp_lt_f32_e64 s[0:1], 0, v13
	s_nop 1
	v_cndmask_b32_e64 v13, v52, v53, s[0:1]
	v_mul_f32_e32 v52, 0x37800000, v13
	v_cndmask_b32_e32 v13, v13, v52, vcc
	v_cmp_class_f32_e32 vcc, v12, v104
	s_nop 1
	v_cndmask_b32_e32 v12, v13, v12, vcc
	v_div_scale_f32 v13, s[0:1], v12, v12, 1.0
	v_rcp_f32_e32 v52, v13
	s_nop 0
	v_fma_f32 v53, -v13, v52, 1.0
	v_fmac_f32_e32 v52, v53, v52
	v_div_scale_f32 v53, vcc, 1.0, v12, 1.0
	v_mul_f32_e32 v54, v53, v52
	v_fma_f32 v55, -v13, v54, v53
	v_fmac_f32_e32 v54, v55, v52
	v_fma_f32 v13, -v13, v54, v53
	v_div_fmas_f32 v13, v13, v52, v54
	v_div_fixup_f32 v52, v13, v12, 1.0
	v_pk_mul_f32 v[2:3], v[2:3], v[52:53] op_sel_hi:[1,0]
	v_pk_mul_f32 v[12:13], v[6:7], v[52:53] op_sel_hi:[1,0]
	v_pk_fma_f32 v[2:3], v[214:215], v[2:3], v[218:219]
	v_pk_mul_f32 v[16:17], v[48:49], v[52:53] op_sel_hi:[1,0]
	v_pk_mul_f32 v[4:5], v[4:5], v[52:53] op_sel_hi:[1,0]
	v_pk_mul_f32 v[6:7], v[8:9], v[52:53] op_sel_hi:[1,0]
	v_pk_fma_f32 v[8:9], v[222:223], v[12:13], v[226:227]
	v_pk_mul_f32 v[12:13], v[14:15], v[52:53] op_sel_hi:[1,0]
	v_pk_fma_f32 v[14:15], v[230:231], v[16:17], v[234:235]
	v_pk_mul_f32 v[16:17], v[10:11], v[52:53] op_sel_hi:[1,0]
	v_pk_mul_f32 v[10:11], v[50:51], v[52:53] op_sel_hi:[1,0]
	v_pk_fma_f32 v[4:5], v[216:217], v[4:5], v[220:221]
	v_pk_fma_f32 v[6:7], v[224:225], v[6:7], v[228:229]
	v_pk_fma_f32 v[12:13], v[232:233], v[12:13], v[236:237]
	v_pk_fma_f32 v[10:11], v[240:241], v[10:11], v[244:245]
	v_pk_fma_f32 v[16:17], v[238:239], v[16:17], v[242:243]
	v_cvt_pk_bf16_f32 v18, v2, v3
	v_cvt_pk_bf16_f32 v19, v4, v5
	v_lshl_add_u64 v[20:21], v[90:91], 0, s[14:15]
	global_store_dwordx2 v[20:21], v[18:19], off offset:2048 nt
	v_cvt_pk_bf16_f32 v18, v8, v9
	v_cvt_pk_bf16_f32 v19, v6, v7
	global_store_dwordx2 v[20:21], v[18:19], off offset:2560 nt
	v_cvt_pk_bf16_f32 v18, v14, v15
	v_cvt_pk_bf16_f32 v19, v12, v13
	global_store_dwordx2 v[20:21], v[18:19], off offset:3072 nt
	v_cvt_pk_bf16_f32 v18, v16, v17
	v_cvt_pk_bf16_f32 v19, v10, v11
	global_store_dwordx2 v[20:21], v[18:19], off offset:3584 nt
	v_add_co_u32_e32 v50, vcc, s27, v92
	s_add_i32 s6, s6, s8
	s_nop 0
	v_addc_co_u32_e32 v51, vcc, 0, v93, vcc
	v_add_co_u32_e32 v52, vcc, s28, v92
	s_add_i32 s18, s18, s19
	s_nop 0
	v_addc_co_u32_e32 v53, vcc, 0, v93, vcc
	v_add_co_u32_e32 v54, vcc, 0x30c0000, v92
	s_add_i32 s21, s21, s24
	v_lshl_add_u64 v[90:91], v[90:91], 0, s[16:17]
	v_addc_co_u32_e32 v55, vcc, 0, v93, vcc
	v_lshl_add_u64 v[60:61], v[60:61], 0, s[16:17]
	v_pk_fma_f32 v[4:5], v[4:5], v[112:113], v[128:129]
	v_pk_fma_f32 v[2:3], v[2:3], v[110:111], v[126:127]
	v_pk_fma_f32 v[6:7], v[6:7], v[116:117], v[132:133]
	v_pk_fma_f32 v[8:9], v[8:9], v[114:115], v[130:131]
	v_pk_fma_f32 v[12:13], v[12:13], v[120:121], v[136:137]
	v_pk_fma_f32 v[14:15], v[14:15], v[118:119], v[134:135]
	v_pk_fma_f32 v[10:11], v[10:11], v[124:125], v[140:141]
	v_pk_fma_f32 v[16:17], v[16:17], v[122:123], v[138:139]
	v_cvt_pk_bf16_f32 v2, v2, v3
	v_cvt_pk_bf16_f32 v3, v4, v5
	v_cvt_pk_bf16_f32 v4, v8, v9
	v_cvt_pk_bf16_f32 v5, v6, v7
	v_cvt_pk_bf16_f32 v6, v14, v15
	v_cvt_pk_bf16_f32 v7, v12, v13
	v_cvt_pk_bf16_f32 v8, v16, v17
	v_cvt_pk_bf16_f32 v9, v10, v11
	global_store_dwordx2 v[92:93], v[2:3], off
	global_store_dwordx2 v[50:51], v[4:5], off
	global_store_dwordx2 v[52:53], v[6:7], off
	global_store_dwordx2 v[54:55], v[8:9], off
	v_lshl_add_u64 v[92:93], v[92:93], 0, s[12:13]
	s_cmp_lt_i32 s6, 0x8000
	s_cbranch_scc1 .Lp4_loop
	s_cmp_lt_i32 s6, 0x8200
	s_cbranch_scc0 .LBB0_342
	s_branch .LBB0_334

; #define LAS __attribute__((address_space(3)))
; __device__ __forceinline__ void scan_pair(Frame& F, const int g, const int b, unsigned long long& pt0, unsigned long long& pt1) {
;     ...
;     const f32x4 za = *(const f32x4*)((const float*)(F.ws + WS_ZA) + ((size_t)(r * NG + g) * 64 + n) * 4);
;     const float aTr = za[2], aTi = za[3];
;     float hr, hi;
;     LAS unsigned char* uct = F.lds + 16384;
;     LAS float* sctx = (LAS float*)(F.lds + 16384 + 8 * 1040);
;     {   const int tt = (F.wave * 64 + n) >> 1, hf = n & 1;
;         f32x4 a0 = {0.f, 0.f, 0.f, 0.f}, a1 = a0;
; #pragma unroll
;         for (int ks = 0; ks < 4; ++ks) { const f32x4* rp = (const f32x4*)((const float*)(F.ws + WS_UCS) + ((((size_t)g * 4 + ks) * RC + b * CTXL + tt) * 16) + hf * 8); a0 += rp[0]; a1 += rp[1]; }
;         u32x4 w; w.x = pk2(a0[0], a0[1]); w.y = pk2(a0[2], a0[3]); w.z = pk2(a1[0], a1[1]); w.w = pk2(a1[2], a1[3]);
;         *(LAS u32x4*)(uct + (tt >> 5) * 1040 + ((tt & 31) * 16 + hf * 8) * 2) = w; }
;     __syncthreads();
;     {   const int kg = n >> 4, cl = n & 15;
;         const char* m2 = (const char*)(F.ws + WS_M2 + (size_t)g * MiB);
; #pragma unroll
;         for (int jb = 0; jb < 2; ++jb) { const int j = (F.wave * 2 + jb) * 16 + cl;
;             bf16x8 bm[16];
; #pragma unroll
;             for (int kt = 0; kt < 16; ++kt) bm[kt] = *(const bf16x8*)(m2 + ((size_t)((kt * 32 + kg * 8) >> 6) * 256 + j) * 128 + ((kt * 32 + kg * 8) & 63) * 2);
;             f32x4 d = {0.f, 0.f, 0.f, 0.f};
; #pragma unroll
;             for (int kt = 0; kt < 16; ++kt) { const bf16x8 au = *(const LAS bf16x8*)(uct + (cl & 7) * 1040 + (kt * 32 + kg * 8) * 2);
;                 d = __builtin_amdgcn_mfma_f32_16x16x32_bf16(au, bm[kt], d, 0, 0, 0); }
.LBB0_545:
	v_readlane_b32 s10, v252, 0
	s_add_i32 s4, s10, s60
	s_ashr_i32 s5, s4, 31
	s_lshl_b64 s[4:5], s[4:5], 10
	v_readlane_b32 s6, v253, 53
	v_mov_b32_e32 v74, v209
	s_add_u32 s4, s6, s4
	v_readlane_b32 s6, v253, 54
	s_waitcnt vmcnt(0)
	s_barrier
	s_waitcnt vmcnt(0)
	s_waitcnt vmcnt(0)
	s_barrier
	s_addc_u32 s5, s6, s5
	v_ashrrev_i32_e32 v75, 31, v74
	v_lshl_add_u64 v[2:3], v[74:75], 4, s[4:5]
	v_readlane_b32 s4, v253, 55
	global_load_dwordx4 v[246:249], v[2:3], off
	s_lshl_b32 s6, s2, 8
	v_add_u32_e32 v24, s4, v74
	v_ashrrev_i32_e32 v2, 1, v24
	s_lshl_b64 s[4:5], s[60:61], 11
	v_ashrrev_i32_e32 v3, 31, v2
	s_or_b32 s4, s4, s6
	v_and_b32_e32 v25, 1, v74
	v_lshl_add_u64 v[6:7], s[4:5], 0, v[2:3]
	v_readlane_b32 s4, v253, 56
	v_lshlrev_b32_e32 v130, 5, v25
	v_readlane_b32 s5, v253, 57
	v_lshlrev_b64 v[6:7], 6, v[6:7]
	v_ashrrev_i32_e32 v3, 6, v24
	v_lshl_add_u64 v[8:9], s[4:5], 0, v[130:131]
	v_lshl_add_u64 v[14:15], v[8:9], 0, v[6:7]
	v_lshl_add_u64 v[202:203], v[14:15], 0, s[8:9]
	s_mov_b64 s[4:5], 0x10000
	v_lshl_add_u64 v[204:205], v[14:15], 0, s[4:5]
	s_mov_b64 s[4:5], 0x18000
	v_lshl_add_u64 v[206:207], v[14:15], 0, s[4:5]
	global_load_dwordx4 v[170:173], v[14:15], off
	global_load_dwordx4 v[174:177], v[14:15], off offset:16
	global_load_dwordx4 v[178:181], v[202:203], off
	global_load_dwordx4 v[182:185], v[202:203], off offset:16
	global_load_dwordx4 v[186:189], v[204:205], off
	global_load_dwordx4 v[190:193], v[204:205], off offset:16
	global_load_dwordx4 v[194:197], v[206:207], off
	global_load_dwordx4 v[198:201], v[206:207], off offset:16
	v_lshlrev_b32_e32 v2, 5, v2
	v_and_b32_e32 v2, 0x3e0, v2
	v_and_b32_e32 v169, 15, v74
	v_ashrrev_i32_e32 v168, 4, v74
	v_and_b32_e32 v130, 0x70, v74
	v_mov_b32_e32 v123, v131
	v_mov_b32_e32 v83, v131
	v_mov_b32_e32 v89, v131
	v_mov_b32_e32 v95, v131
	v_mov_b32_e32 v101, v131
	v_mov_b32_e32 v107, v131
	v_mov_b32_e32 v121, v131
	v_mov_b32_e32 v113, v131
	v_readlane_b32 s11, v252, 1
	s_movk_i32 s4, 0x410
	v_mul_lo_u32 v3, v3, s4
	v_add_u32_e32 v3, 0, v3
	v_cmp_gt_i32_e32 vcc, 2, v168
	s_waitcnt vmcnt(6)
	v_pk_add_f32 v[22:23], v[174:175], 0 op_sel_hi:[1,0]
	v_pk_add_f32 v[18:19], v[170:171], 0 op_sel_hi:[1,0]
	v_pk_add_f32 v[16:17], v[172:173], 0 op_sel_hi:[1,0]
	v_pk_add_f32 v[20:21], v[176:177], 0 op_sel_hi:[1,0]
	s_waitcnt vmcnt(4)
	v_pk_add_f32 v[18:19], v[18:19], v[178:179]
	v_pk_add_f32 v[22:23], v[22:23], v[182:183]
	v_pk_add_f32 v[16:17], v[16:17], v[180:181]
	v_pk_add_f32 v[20:21], v[20:21], v[184:185]
	s_waitcnt vmcnt(2)
	v_pk_add_f32 v[18:19], v[18:19], v[186:187]
	v_pk_add_f32 v[22:23], v[22:23], v[190:191]
	v_pk_add_f32 v[16:17], v[16:17], v[188:189]
	v_pk_add_f32 v[20:21], v[20:21], v[192:193]
	s_waitcnt vmcnt(0)
	v_pk_add_f32 v[8:9], v[16:17], v[196:197]
	v_pk_add_f32 v[6:7], v[18:19], v[194:195]
	v_pk_add_f32 v[10:11], v[22:23], v[198:199]
	v_pk_add_f32 v[12:13], v[20:21], v[200:201]
	v_cvt_pk_bf16_f32 v6, v6, v7
	v_cvt_pk_bf16_f32 v7, v8, v9
	v_cvt_pk_bf16_f32 v8, v10, v11
	v_lshlrev_b32_e32 v10, 4, v25
	v_cvt_pk_bf16_f32 v9, v12, v13
	v_add3_u32 v2, v3, v2, v10
	v_and_b32_e32 v3, -16, v74
	ds_write_b128 v2, v[6:9] offset:16384
	v_and_b32_e32 v2, 7, v74
	v_add_u32_e32 v124, 0, v3
	v_mad_u32_u24 v8, v2, s4, v124
	v_readlane_b32 s4, v253, 58
	v_mov_b32_e32 v3, v131
	v_ashrrev_i32_e32 v10, 7, v74
	v_or_b32_e32 v2, s4, v169
	v_lshlrev_b64 v[6:7], 7, v[2:3]
	v_ashrrev_i32_e32 v11, 31, v10
	v_lshlrev_b32_e32 v9, 3, v168
	v_lshl_add_u64 v[6:7], s[82:83], 0, v[6:7]
	v_lshlrev_b64 v[76:77], 15, v[10:11]
	v_lshl_add_u64 v[10:11], v[6:7], 0, v[76:77]
	v_add_u32_e32 v3, 32, v9
	v_lshl_add_u64 v[10:11], v[10:11], 0, v[130:131]
	v_ashrrev_i32_e32 v14, 6, v3
	s_waitcnt lgkmcnt(0)
	s_barrier
	global_load_dwordx4 v[10:13], v[10:11], off
	v_ashrrev_i32_e32 v15, 31, v14
	v_lshlrev_b64 v[118:119], 15, v[14:15]
	v_lshlrev_b32_e32 v3, 1, v3
	v_lshl_add_u64 v[14:15], v[6:7], 0, v[118:119]
	v_and_b32_e32 v122, 0x70, v3
	v_add_u32_e32 v3, 64, v9
	v_lshl_add_u64 v[14:15], v[14:15], 0, v[122:123]
	v_ashrrev_i32_e32 v18, 6, v3
	global_load_dwordx4 v[14:17], v[14:15], off
	v_ashrrev_i32_e32 v19, 31, v18
	v_lshlrev_b64 v[78:79], 15, v[18:19]
	v_add_u32_e32 v3, 0x60, v9
	v_lshl_add_u64 v[18:19], v[6:7], 0, v[78:79]
	v_ashrrev_i32_e32 v22, 6, v3
	v_lshl_add_u64 v[18:19], v[18:19], 0, v[130:131]
	v_ashrrev_i32_e32 v23, 31, v22
	global_load_dwordx4 v[18:21], v[18:19], off
	v_lshlrev_b64 v[80:81], 15, v[22:23]
	v_lshlrev_b32_e32 v3, 1, v3
	v_lshl_add_u64 v[22:23], v[6:7], 0, v[80:81]
	v_and_b32_e32 v82, 0x70, v3
	v_lshl_add_u64 v[22:23], v[22:23], 0, v[82:83]
	v_add_u32_e32 v3, 0x80, v9
	global_load_dwordx4 v[34:37], v[22:23], off
	v_ashrrev_i32_e32 v22, 6, v3
	v_ashrrev_i32_e32 v23, 31, v22
	v_lshlrev_b64 v[84:85], 15, v[22:23]
	v_lshl_add_u64 v[22:23], v[6:7], 0, v[84:85]
	v_lshl_add_u64 v[22:23], v[22:23], 0, v[130:131]
	global_load_dwordx4 v[42:45], v[22:23], off
	v_add_u32_e32 v3, 0xa0, v9
	v_ashrrev_i32_e32 v22, 6, v3
	v_ashrrev_i32_e32 v23, 31, v22
	v_lshlrev_b64 v[86:87], 15, v[22:23]
	v_lshlrev_b32_e32 v3, 1, v3
	v_lshl_add_u64 v[22:23], v[6:7], 0, v[86:87]
	v_and_b32_e32 v88, 0x70, v3
	v_lshl_add_u64 v[22:23], v[22:23], 0, v[88:89]
	v_add_u32_e32 v3, 0xc0, v9
	global_load_dwordx4 v[46:49], v[22:23], off
	v_ashrrev_i32_e32 v22, 6, v3
	v_ashrrev_i32_e32 v23, 31, v22
	v_lshlrev_b64 v[90:91], 15, v[22:23]
	v_lshl_add_u64 v[22:23], v[6:7], 0, v[90:91]
	v_lshl_add_u64 v[22:23], v[22:23], 0, v[130:131]
	v_add_u32_e32 v3, 0xe0, v9
	global_load_dwordx4 v[50:53], v[22:23], off
	v_ashrrev_i32_e32 v22, 6, v3
	v_ashrrev_i32_e32 v23, 31, v22
	v_lshlrev_b64 v[92:93], 15, v[22:23]
	v_lshlrev_b32_e32 v3, 1, v3
; #define LAS __attribute__((address_space(3)))
; __device__ __forceinline__ void scan_pair(Frame& F, const int g, const int b, unsigned long long& pt0, unsigned long long& pt1) {
;     ...
;     {   const int kg = n >> 4, cl = n & 15;
;         const char* m2 = (const char*)(F.ws + WS_M2 + (size_t)g * MiB);
; #pragma unroll
;         for (int jb = 0; jb < 2; ++jb) { const int j = (F.wave * 2 + jb) * 16 + cl;
;             bf16x8 bm[16];
; #pragma unroll
;             for (int kt = 0; kt < 16; ++kt) bm[kt] = *(const bf16x8*)(m2 + ((size_t)((kt * 32 + kg * 8) >> 6) * 256 + j) * 128 + ((kt * 32 + kg * 8) & 63) * 2);
;             f32x4 d = {0.f, 0.f, 0.f, 0.f};
; #pragma unroll
;             for (int kt = 0; kt < 16; ++kt) { const bf16x8 au = *(const LAS bf16x8*)(uct + (cl & 7) * 1040 + (kt * 32 + kg * 8) * 2);
;                 d = __builtin_amdgcn_mfma_f32_16x16x32_bf16(au, bm[kt], d, 0, 0, 0); }
;             if (kg < 2) *(LAS f32x4*)(sctx + j * 8 + 4 * kg) = d; } }
	v_lshl_add_u64 v[22:23], v[6:7], 0, v[92:93]
	v_and_b32_e32 v94, 0x70, v3
	v_lshl_add_u64 v[22:23], v[22:23], 0, v[94:95]
	v_add_u32_e32 v3, 0x100, v9
	global_load_dwordx4 v[58:61], v[22:23], off
	v_ashrrev_i32_e32 v22, 6, v3
	v_ashrrev_i32_e32 v23, 31, v22
	v_lshlrev_b64 v[96:97], 15, v[22:23]
	v_lshl_add_u64 v[22:23], v[6:7], 0, v[96:97]
	v_lshl_add_u64 v[22:23], v[22:23], 0, v[130:131]
	v_add_u32_e32 v3, 0x120, v9
	global_load_dwordx4 v[70:73], v[22:23], off
	v_ashrrev_i32_e32 v22, 6, v3
	v_ashrrev_i32_e32 v23, 31, v22
	v_lshlrev_b64 v[98:99], 15, v[22:23]
	v_lshlrev_b32_e32 v3, 1, v3
	v_lshl_add_u64 v[22:23], v[6:7], 0, v[98:99]
	v_and_b32_e32 v100, 0x70, v3
	v_lshl_add_u64 v[22:23], v[22:23], 0, v[100:101]
	v_add_u32_e32 v3, 0x140, v9
	global_load_dwordx4 v[126:129], v[22:23], off
	v_ashrrev_i32_e32 v22, 6, v3
	v_ashrrev_i32_e32 v23, 31, v22
	v_lshlrev_b64 v[102:103], 15, v[22:23]
	v_lshl_add_u64 v[22:23], v[6:7], 0, v[102:103]
	v_lshl_add_u64 v[22:23], v[22:23], 0, v[130:131]
	v_add_u32_e32 v3, 0x160, v9
	global_load_dwordx4 v[132:135], v[22:23], off
	v_ashrrev_i32_e32 v22, 6, v3
	v_ashrrev_i32_e32 v23, 31, v22
	v_lshlrev_b64 v[104:105], 15, v[22:23]
	v_lshlrev_b32_e32 v3, 1, v3
	v_lshl_add_u64 v[22:23], v[6:7], 0, v[104:105]
	v_and_b32_e32 v106, 0x70, v3
	v_lshl_add_u64 v[22:23], v[22:23], 0, v[106:107]
	v_add_u32_e32 v3, 0x180, v9
	global_load_dwordx4 v[136:139], v[22:23], off
	v_ashrrev_i32_e32 v22, 6, v3
	v_ashrrev_i32_e32 v23, 31, v22
	v_lshlrev_b64 v[110:111], 15, v[22:23]
	v_lshl_add_u64 v[22:23], v[6:7], 0, v[110:111]
	v_lshl_add_u64 v[22:23], v[22:23], 0, v[130:131]
	v_add_u32_e32 v3, 0x1a0, v9
	global_load_dwordx4 v[140:143], v[22:23], off
	v_ashrrev_i32_e32 v22, 6, v3
	v_ashrrev_i32_e32 v23, 31, v22
	v_lshlrev_b64 v[114:115], 15, v[22:23]
	v_lshlrev_b32_e32 v3, 1, v3
	v_lshl_add_u64 v[22:23], v[6:7], 0, v[114:115]
	v_and_b32_e32 v120, 0x70, v3
	v_lshl_add_u64 v[22:23], v[22:23], 0, v[120:121]
	global_load_dwordx4 v[144:147], v[22:23], off
	v_add_u32_e32 v3, 0x1c0, v9
	v_ashrrev_i32_e32 v22, 6, v3
	v_ashrrev_i32_e32 v23, 31, v22
	v_lshlrev_b64 v[116:117], 15, v[22:23]
	v_lshl_add_u64 v[22:23], v[6:7], 0, v[116:117]
	v_lshl_add_u64 v[22:23], v[22:23], 0, v[130:131]
	v_add_u32_e32 v3, 0x1e0, v9
	global_load_dwordx4 v[148:151], v[22:23], off
	v_ashrrev_i32_e32 v22, 6, v3
	ds_read_b128 v[66:69], v8 offset:16384
	v_ashrrev_i32_e32 v23, 31, v22
	v_lshlrev_b64 v[108:109], 15, v[22:23]
	v_lshlrev_b32_e32 v3, 1, v3
	v_lshl_add_u64 v[6:7], v[6:7], 0, v[108:109]
	v_and_b32_e32 v112, 0x70, v3
	v_lshl_add_u64 v[6:7], v[6:7], 0, v[112:113]
	ds_read_b128 v[22:25], v8 offset:16448
	global_load_dwordx4 v[152:155], v[6:7], off
	ds_read_b128 v[26:29], v8 offset:16512
	ds_read_b128 v[30:33], v8 offset:16576
	s_waitcnt vmcnt(15) lgkmcnt(3)
	v_mfma_f32_16x16x32_bf16 v[10:13], v[66:69], v[10:13], 0
	ds_read_b128 v[38:41], v8 offset:16640
	ds_read_b128 v[54:57], v8 offset:16832
	ds_read_b128 v[62:65], v8 offset:16896
	s_waitcnt vmcnt(14) lgkmcnt(5)
	v_mfma_f32_16x16x32_bf16 v[10:13], v[22:25], v[14:17], v[10:13]
	ds_read_b128 v[14:17], v8 offset:17216
	s_waitcnt vmcnt(13) lgkmcnt(5)
	v_mfma_f32_16x16x32_bf16 v[10:13], v[26:29], v[18:21], v[10:13]
	ds_read_b128 v[18:21], v8 offset:17152
	s_waitcnt vmcnt(12) lgkmcnt(5)
	v_mfma_f32_16x16x32_bf16 v[10:13], v[30:33], v[34:37], v[10:13]
	ds_read_b128 v[34:37], v8 offset:17088
	s_waitcnt vmcnt(11) lgkmcnt(5)
	v_mfma_f32_16x16x32_bf16 v[10:13], v[38:41], v[42:45], v[10:13]
	ds_read_b128 v[42:45], v8 offset:16704
	s_waitcnt vmcnt(10) lgkmcnt(0)
	v_mfma_f32_16x16x32_bf16 v[10:13], v[42:45], v[46:49], v[10:13]
	ds_read_b128 v[46:49], v8 offset:16768
	s_waitcnt vmcnt(9) lgkmcnt(0)
	v_mfma_f32_16x16x32_bf16 v[10:13], v[46:49], v[50:53], v[10:13]
	ds_read_b128 v[50:53], v8 offset:17024
	s_waitcnt vmcnt(8)
	v_mfma_f32_16x16x32_bf16 v[10:13], v[54:57], v[58:61], v[10:13]
	ds_read_b128 v[58:61], v8 offset:16960
	s_waitcnt vmcnt(7)
	v_mfma_f32_16x16x32_bf16 v[10:13], v[62:65], v[70:73], v[10:13]
	s_waitcnt vmcnt(6) lgkmcnt(0)
	v_mfma_f32_16x16x32_bf16 v[10:13], v[58:61], v[126:129], v[10:13]
	s_waitcnt vmcnt(5)
	v_mfma_f32_16x16x32_bf16 v[10:13], v[50:53], v[132:135], v[10:13]
	s_waitcnt vmcnt(4)
	v_mfma_f32_16x16x32_bf16 v[10:13], v[34:37], v[136:139], v[10:13]
	s_waitcnt vmcnt(3)
	v_mfma_f32_16x16x32_bf16 v[10:13], v[18:21], v[140:143], v[10:13]
	s_waitcnt vmcnt(2)
	v_mfma_f32_16x16x32_bf16 v[70:73], v[14:17], v[144:147], v[10:13]
	s_nop 5
	ds_read_b128 v[10:13], v8 offset:17280
	ds_read_b128 v[6:9], v8 offset:17344
	s_waitcnt vmcnt(1) lgkmcnt(1)
	v_mfma_f32_16x16x32_bf16 v[70:73], v[10:13], v[148:151], v[70:73]
	s_waitcnt vmcnt(0) lgkmcnt(0)
; #define LAS __attribute__((address_space(3)))
; __device__ __forceinline__ void scan_pair(Frame& F, const int g, const int b, unsigned long long& pt0, unsigned long long& pt1) {
;     ...
;         for (int jb = 0; jb < 2; ++jb) { const int j = (F.wave * 2 + jb) * 16 + cl;
;             bf16x8 bm[16];
; #pragma unroll
;             for (int kt = 0; kt < 16; ++kt) bm[kt] = *(const bf16x8*)(m2 + ((size_t)((kt * 32 + kg * 8) >> 6) * 256 + j) * 128 + ((kt * 32 + kg * 8) & 63) * 2);
;             f32x4 d = {0.f, 0.f, 0.f, 0.f};
; #pragma unroll
;             for (int kt = 0; kt < 16; ++kt) { const bf16x8 au = *(const LAS bf16x8*)(uct + (cl & 7) * 1040 + (kt * 32 + kg * 8) * 2);
;                 d = __builtin_amdgcn_mfma_f32_16x16x32_bf16(au, bm[kt], d, 0, 0, 0); }
;             if (kg < 2) *(LAS f32x4*)(sctx + j * 8 + 4 * kg) = d; } }
;     __syncthreads();
;     float h0r = 0.f, h0i = 0.f;
;     {   const LAS f32x4* sre = (const LAS f32x4*)(sctx + (r * 128 + n) * 8); const LAS f32x4* sim = (const LAS f32x4*)(sctx + (r * 128 + 64 + n) * 8);
;         const f32x4 re0 = sre[0], re1 = sre[1], im0 = sim[0], im1 = sim[1];
;         if (r == 0) {
; #pragma unroll
;             for (int c = 0; c < 8; ++c) cmul_acc(h0r, h0i, aTr, aTi, c < 4 ? re0[c & 3] : re1[c & 3], c < 4 ? im0[c & 3] : im1[c & 3]);
;         } else {
; #pragma unroll
;             for (int c = 7; c >= 0; --c) cmul_acc(h0r, h0i, aTr, aTi, c < 4 ? re0[c & 3] : re1[c & 3], c < 4 ? im0[c & 3] : im1[c & 3]); } }
	v_mfma_f32_16x16x32_bf16 v[70:73], v[6:9], v[152:155], v[70:73]
	s_and_saveexec_b64 s[4:5], vcc
	v_lshl_add_u32 v3, v2, 5, v124
	s_nop 5
	ds_write_b128 v3, v[70:73] offset:24704
	s_or_b64 exec, exec, s[4:5]
	v_or_b32_e32 v2, 16, v2
	v_mov_b32_e32 v3, v131
	v_lshlrev_b64 v[70:71], 7, v[2:3]
	v_lshl_add_u64 v[126:127], s[82:83], 0, v[70:71]
	v_lshl_add_u64 v[70:71], v[126:127], 0, v[76:77]
	v_lshl_add_u64 v[70:71], v[70:71], 0, v[130:131]
	global_load_dwordx4 v[170:173], v[70:71], off
	v_lshl_add_u64 v[70:71], v[126:127], 0, v[118:119]
	v_lshl_add_u64 v[70:71], v[70:71], 0, v[122:123]
	global_load_dwordx4 v[174:177], v[70:71], off
	v_lshl_add_u64 v[70:71], v[126:127], 0, v[78:79]
	v_lshl_add_u64 v[70:71], v[70:71], 0, v[130:131]
	global_load_dwordx4 v[178:181], v[70:71], off
	v_lshl_add_u64 v[70:71], v[126:127], 0, v[80:81]
	v_lshl_add_u64 v[70:71], v[70:71], 0, v[82:83]
	global_load_dwordx4 v[182:185], v[70:71], off
	v_lshl_add_u64 v[70:71], v[126:127], 0, v[84:85]
	v_lshl_add_u64 v[70:71], v[70:71], 0, v[130:131]
	global_load_dwordx4 v[186:189], v[70:71], off
	v_lshl_add_u64 v[70:71], v[126:127], 0, v[86:87]
	v_lshl_add_u64 v[70:71], v[70:71], 0, v[88:89]
	global_load_dwordx4 v[190:193], v[70:71], off
	v_lshl_add_u64 v[70:71], v[126:127], 0, v[90:91]
	v_lshl_add_u64 v[70:71], v[70:71], 0, v[130:131]
	global_load_dwordx4 v[194:197], v[70:71], off
	v_lshl_add_u64 v[70:71], v[126:127], 0, v[92:93]
	v_lshl_add_u64 v[70:71], v[70:71], 0, v[94:95]
	global_load_dwordx4 v[198:201], v[70:71], off
	v_lshl_add_u64 v[70:71], v[126:127], 0, v[96:97]
	v_lshl_add_u64 v[70:71], v[70:71], 0, v[130:131]
	global_load_dwordx4 v[202:205], v[70:71], off
	v_lshl_add_u64 v[70:71], v[126:127], 0, v[98:99]
	v_lshl_add_u64 v[70:71], v[70:71], 0, v[100:101]
	global_load_dwordx4 v[210:213], v[70:71], off
	v_lshl_add_u64 v[70:71], v[126:127], 0, v[102:103]
	v_lshl_add_u64 v[70:71], v[70:71], 0, v[130:131]
	global_load_dwordx4 v[214:217], v[70:71], off
	v_lshl_add_u64 v[70:71], v[126:127], 0, v[104:105]
	v_lshl_add_u64 v[70:71], v[70:71], 0, v[106:107]
	global_load_dwordx4 v[218:221], v[70:71], off
	v_lshl_add_u64 v[70:71], v[126:127], 0, v[110:111]
	v_lshl_add_u64 v[70:71], v[70:71], 0, v[130:131]
	global_load_dwordx4 v[222:225], v[70:71], off
	v_lshl_add_u64 v[70:71], v[126:127], 0, v[114:115]
	v_lshl_add_u64 v[70:71], v[70:71], 0, v[120:121]
	global_load_dwordx4 v[226:229], v[70:71], off
	v_lshl_add_u64 v[70:71], v[126:127], 0, v[116:117]
	v_lshl_add_u64 v[70:71], v[70:71], 0, v[130:131]
	global_load_dwordx4 v[230:233], v[70:71], off
	v_lshl_add_u64 v[70:71], v[126:127], 0, v[108:109]
	v_lshl_add_u64 v[70:71], v[70:71], 0, v[112:113]
	global_load_dwordx4 v[234:237], v[70:71], off
	s_waitcnt vmcnt(15)
	v_mfma_f32_16x16x32_bf16 v[66:69], v[66:69], v[170:173], 0
	s_waitcnt vmcnt(14)
	v_mfma_f32_16x16x32_bf16 v[22:25], v[22:25], v[174:177], v[66:69]
	s_waitcnt vmcnt(13)
	v_mfma_f32_16x16x32_bf16 v[22:25], v[26:29], v[178:181], v[22:25]
	s_waitcnt vmcnt(12)
	v_mfma_f32_16x16x32_bf16 v[22:25], v[30:33], v[182:185], v[22:25]
	s_waitcnt vmcnt(11)
	v_mfma_f32_16x16x32_bf16 v[22:25], v[38:41], v[186:189], v[22:25]
	s_waitcnt vmcnt(10)
	v_mfma_f32_16x16x32_bf16 v[22:25], v[42:45], v[190:193], v[22:25]
	s_waitcnt vmcnt(9)
	v_mfma_f32_16x16x32_bf16 v[22:25], v[46:49], v[194:197], v[22:25]
	s_waitcnt vmcnt(8)
	v_mfma_f32_16x16x32_bf16 v[22:25], v[54:57], v[198:201], v[22:25]
	s_waitcnt vmcnt(7)
	v_mfma_f32_16x16x32_bf16 v[22:25], v[62:65], v[202:205], v[22:25]
	s_waitcnt vmcnt(6)
	v_mfma_f32_16x16x32_bf16 v[22:25], v[58:61], v[210:213], v[22:25]
	s_waitcnt vmcnt(5)
	v_mfma_f32_16x16x32_bf16 v[22:25], v[50:53], v[214:217], v[22:25]
	s_waitcnt vmcnt(4)
	v_mfma_f32_16x16x32_bf16 v[22:25], v[34:37], v[218:221], v[22:25]
	s_waitcnt vmcnt(3)
	v_mfma_f32_16x16x32_bf16 v[18:21], v[18:21], v[222:225], v[22:25]
	s_waitcnt vmcnt(2)
	v_mfma_f32_16x16x32_bf16 v[14:17], v[14:17], v[226:229], v[18:21]
	s_waitcnt vmcnt(1)
	v_mfma_f32_16x16x32_bf16 v[10:13], v[10:13], v[230:233], v[14:17]
	s_waitcnt vmcnt(0)
	v_mfma_f32_16x16x32_bf16 v[6:9], v[6:9], v[234:237], v[10:13]
	s_and_saveexec_b64 s[4:5], vcc
	v_readlane_b32 s14, v253, 59
	v_readlane_b32 s15, v253, 60
	v_lshl_add_u32 v2, v2, 5, v124
	s_nop 3
	ds_write_b128 v2, v[6:9] offset:24704
	s_or_b64 exec, exec, s[4:5]
	v_add_u32_e32 v2, s10, v74
	v_lshl_add_u32 v2, v2, 5, 0
	s_waitcnt lgkmcnt(0)
	s_barrier
	ds_read_b128 v[18:21], v2 offset:24704
	ds_read_b128 v[6:9], v2 offset:24720
	ds_read_b128 v[14:17], v2 offset:26752
	ds_read_b128 v[10:13], v2 offset:26768
	v_mov_b32_e32 v4, v248
	v_mov_b32_e32 v5, v249
	v_mul_f32_e32 v2, 0, v4
	v_mul_f32_e32 v29, 0, v5
	v_sub_f32_e32 v28, v2, v29
	v_fmac_f32_e32 v29, 0, v4
	s_and_b64 vcc, exec, s[14:15]
	s_cbranch_vccz .LBB0_552
	s_waitcnt lgkmcnt(2)
	v_mov_b32_e32 v2, v9
	s_waitcnt lgkmcnt(0)
	v_mov_b32_e32 v3, v13
	v_pk_add_f32 v[2:3], v[28:29], v[2:3]
	v_mov_b32_e32 v46, v18
	v_pk_mul_f32 v[22:23], v[4:5], v[2:3]
	v_pk_mul_f32 v[2:3], v[4:5], v[2:3] op_sel:[1,0] op_sel_hi:[0,1]
	v_add_f32_e32 v2, v2, v3
	v_sub_f32_e32 v9, v22, v23
	v_add_f32_e32 v2, v12, v2
	v_add_f32_e32 v22, v8, v9
	v_pk_mul_f32 v[2:3], v[4:5], v[2:3] op_sel:[1,0] op_sel_hi:[0,0]
	v_pk_fma_f32 v[24:25], v[4:5], v[22:23], v[2:3] neg_lo:[0,0,1] neg_hi:[0,0,1]
	v_pk_fma_f32 v[2:3], v[4:5], v[22:23], v[2:3] op_sel_hi:[1,0,1]
	v_mov_b32_e32 v47, v14
	v_mov_b32_e32 v25, v3
	v_mov_b32_e32 v2, v7
	v_mov_b32_e32 v3, v11
	v_pk_add_f32 v[2:3], v[2:3], v[24:25]
	s_nop 0
	v_pk_mul_f32 v[22:23], v[4:5], v[2:3]
	v_pk_mul_f32 v[2:3], v[4:5], v[2:3] op_sel:[1,0] op_sel_hi:[0,1]
	v_add_f32_e32 v2, v2, v3
	v_sub_f32_e32 v9, v22, v23
	v_add_f32_e32 v2, v10, v2
	v_add_f32_e32 v22, v6, v9
	v_pk_mul_f32 v[2:3], v[4:5], v[2:3] op_sel:[1,0] op_sel_hi:[0,0]
	v_pk_fma_f32 v[24:25], v[4:5], v[22:23], v[2:3] neg_lo:[0,0,1] neg_hi:[0,0,1]
	v_pk_fma_f32 v[2:3], v[4:5], v[22:23], v[2:3] op_sel_hi:[1,0,1]
	s_nop 0
	v_mov_b32_e32 v25, v3
	v_mov_b32_e32 v2, v21
	v_mov_b32_e32 v3, v17
	v_pk_add_f32 v[2:3], v[2:3], v[24:25]
	s_nop 0
	v_pk_mul_f32 v[22:23], v[4:5], v[2:3]
	v_pk_mul_f32 v[2:3], v[4:5], v[2:3] op_sel:[1,0] op_sel_hi:[0,1]
	v_add_f32_e32 v2, v2, v3
	v_sub_f32_e32 v9, v22, v23
	v_add_f32_e32 v2, v16, v2
	v_add_f32_e32 v22, v20, v9
	v_pk_mul_f32 v[2:3], v[4:5], v[2:3] op_sel:[1,0] op_sel_hi:[0,0]
	v_pk_fma_f32 v[24:25], v[4:5], v[22:23], v[2:3] neg_lo:[0,0,1] neg_hi:[0,0,1]
	v_pk_fma_f32 v[2:3], v[4:5], v[22:23], v[2:3] op_sel_hi:[1,0,1]
	s_nop 0
	v_mov_b32_e32 v25, v3
	v_mov_b32_e32 v2, v19
	v_mov_b32_e32 v3, v15
	v_pk_add_f32 v[56:57], v[2:3], v[24:25]
	v_mov_b32_e32 v3, v4
	v_mov_b32_e32 v2, v5
	s_cbranch_execz .LBB0_553
	s_mov_b64 s[88:89], 0x7800
	s_mov_b64 s[86:87], 0x7000
	s_mov_b64 s[84:85], 0x6800
	s_mov_b64 s[6:7], 0x6000
	s_mov_b64 s[4:5], 0x5800
	s_mov_b64 s[82:83], 0x5000
	s_mov_b64 s[68:69], 0x4800
	s_mov_b64 s[28:29], 0x4000
	s_branch .LBB0_554

; __device__ __forceinline__ void phase_ln_out(Frame& F) {
;     const int gw = F.bid * 8 + F.wave, NGW = F.G * 8;
;     for (int row = gw; row < RL; row += NGW) {
;         float* src = F.out + (size_t)row * D;
;         f32x4 v[4];
; #pragma unroll
;         for (int j = 0; j < 4; ++j) { const int idx = 256 * j + 4 * F.lane; const u32x2 f = __builtin_nontemporal_load((const u32x2*)((const char*)F.ws + WS_FO + (((((size_t)(row >> 8) * 4 + j) * 256 + (row & 255)) * 256) + 4 * F.lane) * 2));
;             const f32x4 fv = {bf2f(f.x), bf2f(f.x >> 16), bf2f(f.y), bf2f(f.y >> 16)};
;             const u32x2 xb = __builtin_nontemporal_load((const u32x2*)((const char*)src + 2048 + idx * 2));
;             const f32x4 xv = {bf2f(xb.x), bf2f(xb.x >> 16), bf2f(xb.y), bf2f(xb.y >> 16)};
;             v[j] = DN_ALPHA * xv + fv; }
.LBB0_815:
	s_cmp_lt_i32 s26, 11
	s_cselect_b64 s[0:1], -1, 0
	s_and_b64 s[0:1], s[0:1], s[4:5]
	s_andn2_b64 vcc, exec, s[0:1]
	s_cbranch_vccnz .LBB0_819
	s_lshl_b32 s0, s92, 3
	v_readlane_b32 s1, v253, 23
	s_add_i32 s4, s0, s1
	s_cmpk_gt_i32 s4, 0x7fff
	s_cbranch_scc1 .LBB0_819
	v_mbcnt_lo_u32_b32 v0, -1, 0
	v_mbcnt_hi_u32_b32 v0, -1, v0
	v_and_b32_e32 v1, 64, v0
	v_add_u32_e32 v1, 64, v1
	v_xor_b32_e32 v2, 1, v0
	v_cmp_lt_i32_e32 vcc, v2, v1
	v_lshlrev_b32_e32 v8, 3, v209
	v_mov_b32_e32 v9, 0
	v_cndmask_b32_e32 v2, v0, v2, vcc
	v_lshlrev_b32_e32 v38, 2, v2
	v_xor_b32_e32 v2, 2, v0
	v_cmp_lt_i32_e32 vcc, v2, v1
	s_mov_b64 s[0:1], 0xa300000
	s_lshl_b32 s6, s84, 3
	v_cndmask_b32_e32 v2, v0, v2, vcc
	v_lshlrev_b32_e32 v39, 2, v2
	v_xor_b32_e32 v2, 4, v0
	v_cmp_lt_i32_e32 vcc, v2, v1
	v_lshlrev_b32_e32 v18, 4, v209
	v_mov_b32_e32 v19, v9
	v_cndmask_b32_e32 v2, v0, v2, vcc
	v_lshlrev_b32_e32 v40, 2, v2
	v_xor_b32_e32 v2, 8, v0
	v_cmp_lt_i32_e32 vcc, v2, v1
	v_readlane_b32 s16, v253, 7
	v_readlane_b32 s18, v253, 9
	v_cndmask_b32_e32 v2, v0, v2, vcc
	v_lshlrev_b32_e32 v41, 2, v2
	v_xor_b32_e32 v2, 16, v0
	v_cmp_lt_i32_e32 vcc, v2, v1
	v_readlane_b32 s19, v253, 10
	v_readlane_b32 s30, v253, 21
	v_cndmask_b32_e32 v2, v0, v2, vcc
	v_lshlrev_b32_e32 v42, 2, v2
	v_xor_b32_e32 v2, 32, v0
	v_cmp_lt_i32_e32 vcc, v2, v1
	v_readlane_b32 s31, v253, 22
	s_mov_b64 s[18:19], s[30:31]
	v_cndmask_b32_e32 v0, v0, v2, vcc
	v_lshlrev_b32_e32 v43, 2, v0
	v_lshl_add_u64 v[0:1], s[56:57], 0, v[8:9]
	v_lshl_add_u64 v[10:11], v[0:1], 0, s[0:1]
	s_mov_b64 s[0:1], 0xa320000
	v_lshl_add_u64 v[12:13], v[0:1], 0, s[0:1]
	s_mov_b64 s[0:1], 0xa340000
	v_lshl_add_u64 v[14:15], v[0:1], 0, s[0:1]
	s_mov_b64 s[0:1], 0xa360000
	v_lshl_add_u64 v[16:17], v[0:1], 0, s[0:1]
	s_add_u32 s0, s48, 0x1000
	s_addc_u32 s1, s49, 0
	s_add_u32 s8, s50, 0x1000
	s_addc_u32 s9, s51, 0
	v_or_b32_e32 v0, 0x400, v18
	v_mov_b32_e32 v1, v9
	v_lshl_add_u64 v[24:25], s[0:1], 0, v[0:1]
	v_lshl_add_u64 v[26:27], s[8:9], 0, v[0:1]
	v_or_b32_e32 v0, 0x800, v18
	v_lshl_add_u64 v[28:29], s[0:1], 0, v[0:1]
	v_lshl_add_u64 v[30:31], s[8:9], 0, v[0:1]
	v_or_b32_e32 v0, 0xc00, v18
	v_lshl_add_u64 v[20:21], s[0:1], 0, v[18:19]
	v_lshl_add_u64 v[32:33], s[0:1], 0, v[0:1]
	v_readlane_b32 s1, v253, 23
	s_lshl_b32 s0, s92, 12
	s_lshl_b32 s1, s1, 9
	s_ashr_i32 s5, s4, 31
	s_add_i32 s13, s0, s1
	s_lshl_b32 s14, s84, 12
	s_lshl_b64 s[0:1], s[4:5], 12
	v_lshl_add_u64 v[22:23], s[8:9], 0, v[18:19]
	v_lshl_add_u64 v[34:35], s[8:9], 0, v[0:1]
	s_add_u32 s8, s18, s0
	s_addc_u32 s9, s19, s1
	s_ashr_i32 s7, s6, 31
	s_mov_b32 s3, 0
	s_lshl_b64 s[10:11], s[6:7], 12
	s_mov_b32 s12, 0x3fb504f3
	v_mov_b32_e32 v44, 0x3727c5ac
	s_mov_b32 s5, 0xf800000
	v_mov_b32_e32 v45, 0x260
	v_readlane_b32 s17, v253, 8
	v_readlane_b32 s20, v253, 11
	v_readlane_b32 s21, v253, 12
	v_readlane_b32 s22, v253, 13
	v_readlane_b32 s23, v253, 14
	v_readlane_b32 s24, v253, 15
	v_readlane_b32 s25, v253, 16
	v_readlane_b32 s26, v253, 17
	v_readlane_b32 s27, v253, 18
	v_readlane_b32 s28, v253, 19
	v_readlane_b32 s29, v253, 20
	global_load_dwordx4 v[0:3], v[20:21], off
	global_load_dwordx4 v[4:7], v[22:23], off
	global_load_dwordx4 v[46:49], v[24:25], off
	global_load_dwordx4 v[50:53], v[26:27], off
	global_load_dwordx4 v[54:57], v[28:29], off
	global_load_dwordx4 v[58:61], v[30:31], off
	global_load_dwordx4 v[62:65], v[32:33], off
	global_load_dwordx4 v[66:69], v[34:35], off
	v_lshl_add_u64 v[36:37], s[8:9], 0, v[8:9]
	s_ashr_i32 s0, s4, 8
	s_ashr_i32 s1, s0, 31
	s_lshl_b64 s[0:1], s[0:1], 19
	s_and_b32 s2, s13, 0x1fe00
	global_load_dwordx2 v[118:119], v[36:37], off offset:2048 nt
	global_load_dwordx2 v[120:121], v[36:37], off offset:2560 nt
	global_load_dwordx2 v[122:123], v[36:37], off offset:3072 nt
	global_load_dwordx2 v[124:125], v[36:37], off offset:3584 nt
	v_lshl_add_u64 v[36:37], v[10:11], 0, s[0:1]
	v_lshl_add_u64 v[80:81], v[12:13], 0, s[0:1]
	v_lshl_add_u64 v[82:83], v[14:15], 0, s[0:1]
	v_lshl_add_u64 v[84:85], v[16:17], 0, s[0:1]
	v_lshl_add_u64 v[36:37], v[36:37], 0, s[2:3]
	v_lshl_add_u64 v[80:81], v[80:81], 0, s[2:3]
	v_lshl_add_u64 v[82:83], v[82:83], 0, s[2:3]
	v_lshl_add_u64 v[84:85], v[84:85], 0, s[2:3]
	global_load_dwordx2 v[126:127], v[36:37], off nt
	global_load_dwordx2 v[128:129], v[80:81], off nt
	global_load_dwordx2 v[130:131], v[82:83], off nt
	global_load_dwordx2 v[132:133], v[84:85], off nt
	s_waitcnt vmcnt(0)
.LBB0_818:
	s_waitcnt vmcnt(4)
	v_mov_b32_e32 v72, v118
	v_mov_b32_e32 v73, v119
	v_mov_b32_e32 v74, v120
	v_mov_b32_e32 v75, v121
	v_mov_b32_e32 v76, v122
	v_mov_b32_e32 v77, v123
	v_mov_b32_e32 v78, v124
	v_mov_b32_e32 v79, v125
	v_mov_b32_e32 v86, v126
	v_mov_b32_e32 v87, v127
	v_mov_b32_e32 v88, v128
	v_mov_b32_e32 v89, v129
	v_mov_b32_e32 v90, v130
	v_mov_b32_e32 v91, v131
	v_mov_b32_e32 v92, v132
	v_mov_b32_e32 v93, v133
	v_lshl_add_u64 v[70:71], s[8:9], 0, v[18:19]
	s_add_i32 s13, s13, s14
	s_add_i32 s4, s4, s6
	s_add_u32 s8, s8, s10
	s_addc_u32 s9, s9, s11
	s_cmp_lt_i32 s4, 0x8000
	s_cbranch_scc0 .Lp10_nopf
	v_lshl_add_u64 v[36:37], s[8:9], 0, v[8:9]
	s_ashr_i32 s0, s4, 8
	s_ashr_i32 s1, s0, 31
	s_lshl_b64 s[0:1], s[0:1], 19
	s_and_b32 s2, s13, 0x1fe00
	global_load_dwordx2 v[118:119], v[36:37], off offset:2048 nt
	global_load_dwordx2 v[120:121], v[36:37], off offset:2560 nt
	global_load_dwordx2 v[122:123], v[36:37], off offset:3072 nt
	global_load_dwordx2 v[124:125], v[36:37], off offset:3584 nt
	v_lshl_add_u64 v[36:37], v[10:11], 0, s[0:1]
	v_lshl_add_u64 v[80:81], v[12:13], 0, s[0:1]
	v_lshl_add_u64 v[82:83], v[14:15], 0, s[0:1]
	v_lshl_add_u64 v[84:85], v[16:17], 0, s[0:1]
	v_lshl_add_u64 v[36:37], v[36:37], 0, s[2:3]
	v_lshl_add_u64 v[80:81], v[80:81], 0, s[2:3]
	v_lshl_add_u64 v[82:83], v[82:83], 0, s[2:3]
	v_lshl_add_u64 v[84:85], v[84:85], 0, s[2:3]
	global_load_dwordx2 v[126:127], v[36:37], off nt
	global_load_dwordx2 v[128:129], v[80:81], off nt
	global_load_dwordx2 v[130:131], v[82:83], off nt
	global_load_dwordx2 v[132:133], v[84:85], off nt
; __device__ __forceinline__ void ln_row(f32x4 (&v)[4], const float* g, const float* b, int lane) {
;     float s = 0.f;
; #pragma unroll
;     for (int j = 0; j < 4; ++j) s += (v[j][0] + v[j][1]) + (v[j][2] + v[j][3]);
;     const float mean = wave_sum(s) * (1.f / D); float s2 = 0.f;
; __device__ __forceinline__ void phase_ln_out(Frame& F) {
;     ...
; #pragma unroll
;         for (int j = 0; j < 4; ++j) { const int idx = 256 * j + 4 * F.lane; const u32x2 f = __builtin_nontemporal_load((const u32x2*)((const char*)F.ws + WS_FO + (((((size_t)(row >> 8) * 4 + j) * 256 + (row & 255)) * 256) + 4 * F.lane) * 2));
;             const f32x4 fv = {bf2f(f.x), bf2f(f.x >> 16), bf2f(f.y), bf2f(f.y >> 16)};
;             const u32x2 xb = __builtin_nontemporal_load((const u32x2*)((const char*)src + 2048 + idx * 2));
;             const f32x4 xv = {bf2f(xb.x), bf2f(xb.x >> 16), bf2f(xb.y), bf2f(xb.y >> 16)};
;             v[j] = DN_ALPHA * xv + fv; }
;         ln_row(v, F.in[I_LNG] + D, F.in[I_LNB] + D, F.lane);
.Lp10_nopf:
	v_lshlrev_b32_e32 v80, 16, v74
	v_lshlrev_b32_e32 v36, 16, v72
	v_and_b32_e32 v37, 0xffff0000, v72
	v_lshlrev_b32_e32 v72, 16, v73
	v_and_b32_e32 v73, 0xffff0000, v73
	v_and_b32_e32 v81, 0xffff0000, v74
	v_lshlrev_b32_e32 v74, 16, v75
	v_and_b32_e32 v75, 0xffff0000, v75
	v_lshlrev_b32_e32 v94, 16, v86
	v_and_b32_e32 v95, 0xffff0000, v86
	v_lshlrev_b32_e32 v86, 16, v87
	v_and_b32_e32 v87, 0xffff0000, v87
	v_lshlrev_b32_e32 v96, 16, v88
	v_and_b32_e32 v97, 0xffff0000, v88
	v_lshlrev_b32_e32 v88, 16, v89
	v_and_b32_e32 v89, 0xffff0000, v89
	v_lshlrev_b32_e32 v82, 16, v76
	v_and_b32_e32 v83, 0xffff0000, v76
	v_lshlrev_b32_e32 v76, 16, v77
	v_and_b32_e32 v77, 0xffff0000, v77
	v_lshlrev_b32_e32 v84, 16, v78
	v_and_b32_e32 v85, 0xffff0000, v78
	v_lshlrev_b32_e32 v78, 16, v79
	v_and_b32_e32 v79, 0xffff0000, v79
	v_lshlrev_b32_e32 v98, 16, v90
	v_and_b32_e32 v99, 0xffff0000, v90
	v_lshlrev_b32_e32 v90, 16, v91
	v_and_b32_e32 v91, 0xffff0000, v91
	v_lshlrev_b32_e32 v100, 16, v92
	v_and_b32_e32 v101, 0xffff0000, v92
	v_lshlrev_b32_e32 v92, 16, v93
	v_and_b32_e32 v93, 0xffff0000, v93
	v_pk_fma_f32 v[72:73], v[72:73], s[12:13], v[86:87] op_sel_hi:[1,0,1]
	v_pk_fma_f32 v[36:37], v[36:37], s[12:13], v[94:95] op_sel_hi:[1,0,1]
	v_pk_fma_f32 v[74:75], v[74:75], s[12:13], v[88:89] op_sel_hi:[1,0,1]
	v_pk_fma_f32 v[80:81], v[80:81], s[12:13], v[96:97] op_sel_hi:[1,0,1]
	v_pk_fma_f32 v[76:77], v[76:77], s[12:13], v[90:91] op_sel_hi:[1,0,1]
	v_pk_fma_f32 v[78:79], v[78:79], s[12:13], v[92:93] op_sel_hi:[1,0,1]
	v_pk_mov_b32 v[86:87], v[36:37], v[72:73] op_sel:[1,0]
	v_mov_b32_e32 v88, v36
	v_mov_b32_e32 v89, v73
	v_pk_mov_b32 v[90:91], v[80:81], v[74:75] op_sel:[1,0]
	v_mov_b32_e32 v92, v80
	v_mov_b32_e32 v93, v75
	v_pk_add_f32 v[86:87], v[86:87], v[88:89]
	v_pk_add_f32 v[88:89], v[90:91], v[92:93]
	v_pk_fma_f32 v[82:83], v[82:83], s[12:13], v[98:99] op_sel_hi:[1,0,1]
	v_pk_fma_f32 v[84:85], v[84:85], s[12:13], v[100:101] op_sel_hi:[1,0,1]
	v_add_f32_e32 v92, v86, v87
	v_pk_add_f32 v[86:87], v[88:89], v[88:89] op_sel:[0,1] op_sel_hi:[1,0]
	v_add_f32_e32 v94, v82, v83
	v_add_f32_e32 v96, v76, v77
	v_mov_b32_e32 v99, v84
	v_mov_b32_e32 v95, v78
	v_mov_b32_e32 v97, v79
	v_add_f32_e32 v98, 0, v92
	v_mov_b32_e32 v87, v85
	v_pk_add_f32 v[90:91], v[94:95], v[96:97]
	v_pk_add_f32 v[86:87], v[98:99], v[86:87]
	s_nop 0
	v_pk_add_f32 v[86:87], v[86:87], v[90:91]
	s_nop 0
	v_add_f32_e32 v86, v86, v87
	ds_bpermute_b32 v87, v38, v86
	s_waitcnt lgkmcnt(0)
	v_add_f32_e32 v86, v86, v87
	ds_bpermute_b32 v87, v39, v86
	s_waitcnt lgkmcnt(0)
	v_add_f32_e32 v86, v86, v87
	ds_bpermute_b32 v87, v40, v86
	s_waitcnt lgkmcnt(0)
	v_add_f32_e32 v86, v86, v87
	ds_bpermute_b32 v87, v41, v86
	s_waitcnt lgkmcnt(0)
	v_add_f32_e32 v86, v86, v87
	ds_bpermute_b32 v87, v42, v86
	s_waitcnt lgkmcnt(0)
	v_add_f32_e32 v86, v86, v87
	ds_bpermute_b32 v87, v43, v86
	s_waitcnt lgkmcnt(0)
; __device__ __forceinline__ void ln_row(f32x4 (&v)[4], const float* g, const float* b, int lane) {
;     ...
;     const float mean = wave_sum(s) * (1.f / D); float s2 = 0.f;
; #pragma unroll
;     for (int j = 0; j < 4; ++j) { v[j] = v[j] - mean; s2 += (v[j][0] * v[j][0] + v[j][1] * v[j][1]) + (v[j][2] * v[j][2] + v[j][3] * v[j][3]); }
;     const float rstd = 1.0f / sqrtf(wave_sum(s2) * (1.f / D) + LN_EPS);
; #pragma unroll
;     for (int j = 0; j < 4; ++j) { const int idx = 256 * j + 4 * lane; v[j] = v[j] * rstd * *(const f32x4*)(g + idx) + *(const f32x4*)(b + idx); }
; }
; __device__ __forceinline__ void phase_ln_out(Frame& F) {
;     ...
;         ln_row(v, F.in[I_LNG] + D, F.in[I_LNB] + D, F.lane);
; #pragma unroll
;         for (int j = 0; j < 4; ++j) __builtin_nontemporal_store(v[j], (f32x4*)(src + 256 * j + 4 * F.lane));
	v_add_f32_e32 v86, v86, v87
	v_fmamk_f32 v37, v86, 0xba800000, v37
	v_fmac_f32_e32 v36, 0xba800000, v86
	v_fmamk_f32 v73, v86, 0xba800000, v73
	v_fmac_f32_e32 v72, 0xba800000, v86
	v_fmamk_f32 v81, v86, 0xba800000, v81
	v_fmac_f32_e32 v80, 0xba800000, v86
	v_fmamk_f32 v75, v86, 0xba800000, v75
	v_fmac_f32_e32 v74, 0xba800000, v86
	v_fmamk_f32 v83, v86, 0xba800000, v83
	v_fmac_f32_e32 v82, 0xba800000, v86
	v_fmamk_f32 v77, v86, 0xba800000, v77
	v_fmac_f32_e32 v76, 0xba800000, v86
	v_fmamk_f32 v79, v86, 0xba800000, v79
	v_fmac_f32_e32 v78, 0xba800000, v86
	v_fmamk_f32 v85, v86, 0xba800000, v85
	v_fmac_f32_e32 v84, 0xba800000, v86
	v_pk_mul_f32 v[86:87], v[72:73], v[72:73]
	v_pk_mul_f32 v[88:89], v[36:37], v[36:37]
	v_pk_mul_f32 v[90:91], v[74:75], v[74:75]
	v_pk_mul_f32 v[92:93], v[80:81], v[80:81]
	v_pk_mov_b32 v[98:99], v[88:89], v[86:87] op_sel:[1,0]
	v_mov_b32_e32 v89, v87
	v_pk_mov_b32 v[86:87], v[92:93], v[90:91] op_sel:[1,0]
	v_mov_b32_e32 v93, v91
	v_mul_f32_e32 v94, v82, v82
	v_mul_f32_e32 v96, v76, v76
	v_pk_add_f32 v[88:89], v[98:99], v[88:89]
	v_pk_add_f32 v[86:87], v[86:87], v[92:93]
	v_pk_fma_f32 v[90:91], v[82:83], v[82:83], v[94:95] op_sel_hi:[1,1,0]
	v_pk_fma_f32 v[94:95], v[76:77], v[76:77], v[96:97] op_sel_hi:[1,1,0]
	v_pk_add_f32 v[88:89], v[88:89], v[88:89] op_sel_hi:[0,1]
	v_pk_add_f32 v[86:87], v[86:87], v[86:87] op_sel_hi:[0,1]
	v_mul_f32_e32 v90, v84, v84
	v_mul_f32_e32 v94, v85, v85
	v_mul_f32_e32 v88, v78, v78
	v_mul_f32_e32 v86, v79, v79
	v_pk_add_f32 v[90:91], v[90:91], v[94:95]
	v_pk_add_f32 v[86:87], v[88:89], v[86:87]
	s_nop 0
	v_pk_add_f32 v[86:87], v[90:91], v[86:87]
	s_nop 0
	v_add_f32_e32 v86, v86, v87
	ds_bpermute_b32 v87, v38, v86
	s_waitcnt lgkmcnt(0)
	v_add_f32_e32 v86, v86, v87
	ds_bpermute_b32 v87, v39, v86
	s_waitcnt lgkmcnt(0)
	v_add_f32_e32 v86, v86, v87
	ds_bpermute_b32 v87, v40, v86
	s_waitcnt lgkmcnt(0)
	v_add_f32_e32 v86, v86, v87
	ds_bpermute_b32 v87, v41, v86
	s_waitcnt lgkmcnt(0)
	v_add_f32_e32 v86, v86, v87
	ds_bpermute_b32 v87, v42, v86
	s_waitcnt lgkmcnt(0)
	v_add_f32_e32 v86, v86, v87
	ds_bpermute_b32 v87, v43, v86
	s_waitcnt lgkmcnt(0)
	v_add_f32_e32 v86, v86, v87
	v_fmamk_f32 v86, v86, 0x3a800000, v44
	v_mul_f32_e32 v87, 0x4f800000, v86
	v_cmp_gt_f32_e32 vcc, s5, v86
	s_nop 1
	v_cndmask_b32_e32 v86, v86, v87, vcc
	v_sqrt_f32_e32 v87, v86
	s_nop 0
	v_add_u32_e32 v88, -1, v87
	v_add_u32_e32 v89, 1, v87
	v_fma_f32 v90, -v88, v87, v86
	v_fma_f32 v91, -v89, v87, v86
	v_cmp_ge_f32_e64 s[0:1], 0, v90
	s_nop 1
	v_cndmask_b32_e64 v87, v87, v88, s[0:1]
	v_cmp_lt_f32_e64 s[0:1], 0, v91
	s_nop 1
	v_cndmask_b32_e64 v87, v87, v89, s[0:1]
	v_mul_f32_e32 v88, 0x37800000, v87
	v_cndmask_b32_e32 v87, v87, v88, vcc
	v_cmp_class_f32_e32 vcc, v86, v45
	s_nop 1
	v_cndmask_b32_e32 v86, v87, v86, vcc
	v_div_scale_f32 v87, s[0:1], v86, v86, 1.0
	v_rcp_f32_e32 v89, v87
	v_div_scale_f32 v88, vcc, 1.0, v86, 1.0
	v_fma_f32 v90, -v87, v89, 1.0
	v_fmac_f32_e32 v89, v90, v89
	v_mul_f32_e32 v90, v88, v89
	v_fma_f32 v91, -v87, v90, v88
	v_fmac_f32_e32 v90, v91, v89
	v_fma_f32 v87, -v87, v90, v88
	v_div_fmas_f32 v87, v87, v89, v90
	v_div_fixup_f32 v86, v87, v86, 1.0
	v_pk_mul_f32 v[36:37], v[36:37], v[86:87] op_sel_hi:[1,0]
	v_pk_mul_f32 v[72:73], v[72:73], v[86:87] op_sel_hi:[1,0]
	v_pk_mul_f32 v[80:81], v[80:81], v[86:87] op_sel_hi:[1,0]
	v_pk_mul_f32 v[74:75], v[74:75], v[86:87] op_sel_hi:[1,0]
	v_pk_mul_f32 v[82:83], v[82:83], v[86:87] op_sel_hi:[1,0]
	v_pk_mul_f32 v[76:77], v[76:77], v[86:87] op_sel_hi:[1,0]
	v_pk_mul_f32 v[84:85], v[84:85], v[86:87] op_sel_hi:[1,0]
	v_pk_mul_f32 v[78:79], v[78:79], v[86:87] op_sel_hi:[1,0]
	v_pk_fma_f32 v[104:105], v[2:3], v[72:73], v[6:7]
	v_pk_fma_f32 v[102:103], v[0:1], v[36:37], v[4:5]
	v_pk_fma_f32 v[108:109], v[48:49], v[74:75], v[52:53]
	v_pk_fma_f32 v[106:107], v[46:47], v[80:81], v[50:51]
	v_pk_fma_f32 v[112:113], v[56:57], v[76:77], v[60:61]
	v_pk_fma_f32 v[110:111], v[54:55], v[82:83], v[58:59]
	v_pk_fma_f32 v[116:117], v[64:65], v[78:79], v[68:69]
	v_pk_fma_f32 v[114:115], v[62:63], v[84:85], v[66:67]
	global_store_dwordx4 v[70:71], v[102:105], off nt
	global_store_dwordx4 v[70:71], v[106:109], off offset:1024 nt
	global_store_dwordx4 v[70:71], v[110:113], off offset:2048 nt
	global_store_dwordx4 v[70:71], v[114:117], off offset:3072 nt
	s_cmp_lt_i32 s4, 0x8000
	s_cbranch_scc1 .LBB0_818

; __global__ void __launch_bounds__(512, 2) mk_fwd(Args args) {
	.amdhsa_kernel _Z6mk_fwd4Args
		.amdhsa_group_segment_fixed_size 0
		.amdhsa_private_segment_fixed_size 0
		.amdhsa_kernarg_size 464
		.amdhsa_user_sgpr_count 2
		.amdhsa_user_sgpr_dispatch_ptr 0
		.amdhsa_user_sgpr_queue_ptr 0
		.amdhsa_user_sgpr_kernarg_segment_ptr 1
		.amdhsa_user_sgpr_dispatch_id 0
		.amdhsa_user_sgpr_kernarg_preload_length 0
		.amdhsa_user_sgpr_kernarg_preload_offset 0
		.amdhsa_user_sgpr_private_segment_size 0
		.amdhsa_uses_dynamic_stack 0
		.amdhsa_enable_private_segment 0
		.amdhsa_system_sgpr_workgroup_id_x 1
		.amdhsa_system_sgpr_workgroup_id_y 0
		.amdhsa_system_sgpr_workgroup_id_z 0
		.amdhsa_system_sgpr_workgroup_info 0
		.amdhsa_system_vgpr_workitem_id 0
		.amdhsa_next_free_vgpr 254
		.amdhsa_next_free_sgpr 102
		.amdhsa_accum_offset 256
		.amdhsa_reserve_vcc 1
		.amdhsa_float_round_mode_32 0
		.amdhsa_float_round_mode_16_64 0
		.amdhsa_float_denorm_mode_32 3
		.amdhsa_float_denorm_mode_16_64 3
		.amdhsa_dx10_clamp 1
		.amdhsa_ieee_mode 1
		.amdhsa_fp16_overflow 0
		.amdhsa_tg_split 0
		.amdhsa_exception_fp_ieee_invalid_op 0
		.amdhsa_exception_fp_denorm_src 0
		.amdhsa_exception_fp_ieee_div_zero 0
		.amdhsa_exception_fp_ieee_overflow 0
		.amdhsa_exception_fp_ieee_underflow 0
		.amdhsa_exception_fp_ieee_inexact 0
		.amdhsa_exception_int_div_zero 0
	.end_amdhsa_kernel

; __global__ void __launch_bounds__(512, 2) mk_fwd(Args args) {
amdhsa.kernels:
  - .agpr_count:     0
    .args:
      - .offset:         0
        .size:           208
        .value_kind:     by_value
      - .offset:         208
        .size:           4
        .value_kind:     hidden_block_count_x
      - .offset:         212
        .size:           4
        .value_kind:     hidden_block_count_y
      - .offset:         216
        .size:           4
        .value_kind:     hidden_block_count_z
      - .offset:         220
        .size:           2
        .value_kind:     hidden_group_size_x
      - .offset:         222
        .size:           2
        .value_kind:     hidden_group_size_y
      - .offset:         224
        .size:           2
        .value_kind:     hidden_group_size_z
      - .offset:         226
        .size:           2
        .value_kind:     hidden_remainder_x
      - .offset:         228
        .size:           2
        .value_kind:     hidden_remainder_y
      - .offset:         230
        .size:           2
        .value_kind:     hidden_remainder_z
      - .offset:         248
        .size:           8
        .value_kind:     hidden_global_offset_x
      - .offset:         256
        .size:           8
        .value_kind:     hidden_global_offset_y
      - .offset:         264
        .size:           8
        .value_kind:     hidden_global_offset_z
      - .offset:         272
        .size:           2
        .value_kind:     hidden_grid_dims
      - .offset:         328
        .size:           4
        .value_kind:     hidden_dynamic_lds_size
    .group_segment_fixed_size: 0
    .kernarg_segment_align: 8
    .kernarg_segment_size: 464
    .language:       OpenCL C
    .language_version:
      - 2
      - 0
    .max_flat_workgroup_size: 512
    .name:           _Z6mk_fwd4Args
    .private_segment_fixed_size: 0
    .sgpr_count:     108
    .sgpr_spill_count: 74
    .symbol:         _Z6mk_fwd4Args.kd
    .uniform_work_group_size: 1
    .uses_dynamic_stack: false
    .vgpr_count:     254
    .vgpr_spill_count: 0
    .wavefront_size: 64
